# P8: each wave keeps half of the state slice (no redundant state update), bf16 state halves handed over through LDS; two barriers per step
# speedup vs baseline: 1.0360x; 1.0005x over previous
.LBB0_906:
	s_cmp_lt_i32 s90, 9
	s_cselect_b64 s[2:3], -1, 0
	s_and_b64 s[38:39], s[2:3], s[0:1]
	s_andn2_b64 vcc, exec, s[38:39]
	s_cbranch_vccnz .LBB0_998
	s_mov_b64 s[70:71], s[62:63]
	s_mov_b32 s68, s59
	s_mov_b64 s[66:67], s[60:61]
	s_cmpk_gt_i32 s58, 0xff
	v_readfirstlane_b32 s20, v0
	s_cbranch_scc1 .LBB0_997
	v_readlane_b32 s15, v251, 48
	v_readfirstlane_b32 s35, v0
	s_lshr_b32 s35, s35, 6
	s_and_b32 s36, s35, 3
	s_lshr_b32 s37, s35, 2
	s_and_b32 s31, s15, 1
	s_bfe_u32 s73, s15, 0x20001
	s_bfe_u32 s74, s15, 0x20003
	s_lshr_b32 s72, s15, 5
	s_lshl_b32 s33, s72, 8
	s_addk_i32 s33, 0x4000
	s_lshl_b32 s34, s72, 11
	s_addk_i32 s34, 0xff00
	s_movk_i32 s48, 0x1800
	s_movk_i32 s49, 0x400
	s_cmp_eq_u32 s31, 0
	s_cselect_b32 s30, s48, s49
	s_lshl_b32 s48, s73, 8
	s_add_u32 s49, s88, 0xa27d000
	s_addc_u32 s52, s89, 0
	s_cmp_eq_u32 s31, 0
	s_cselect_b32 s16, s96, s49
	s_cselect_b32 s17, s97, s52
	s_add_u32 s16, s16, s48
	s_addc_u32 s17, s17, 0
	s_add_u32 s49, s88, 0xb27d000
	s_addc_u32 s52, s89, 0
	s_add_u32 s53, s96, 0x400
	s_addc_u32 s64, s97, 0
	s_cmp_eq_u32 s31, 0
	s_cselect_b32 s18, s53, s49
	s_cselect_b32 s19, s64, s52
	s_add_u32 s18, s18, s48
	s_addc_u32 s19, s19, 0
	s_lshl_b32 s49, s73, 9
	s_lshl_b32 s52, s74, 7
	s_add_i32 s49, s49, s52
	s_add_i32 s52, s49, 0x800
	s_add_u32 s20, s96, s52
	s_addc_u32 s21, s97, 0
	v_readlane_b32 s28, v251, 34
	v_readlane_b32 s29, v251, 35
	s_lshl_b32 s52, s31, 25
	s_add_i32 s52, s52, s49
	s_add_u32 s28, s28, s52
	s_addc_u32 s29, s29, 0
	s_lshl_b32 s49, s31, 3
	s_add_i32 s49, s49, s72
	s_lshl_b32 s49, s49, 2
	s_add_i32 s49, s49, s73
	s_mul_i32 s49, s49, 0x4800
	s_add_u32 s22, s88, 0x115d000
	s_addc_u32 s23, s89, 0
	s_add_u32 s22, s22, s49
	s_addc_u32 s23, s23, 0
	v_bfe_u32 v94, v0, 4, 2
	v_lshrrev_b32_e32 v95, 2, v186
	v_and_b32_e32 v96, 3, v186
	v_mov_b32_e32 v97, 272
	v_mul_u32_u24_e32 v98, v186, v97
	v_lshl_add_u32 v182, v94, 4, v98
	v_lshl_add_u32 v183, v94, 3, v98
	v_mov_b32_e32 v97, 288
	v_mul_u32_u24_e32 v98, v186, v97
	v_lshl_add_u32 v242, v94, 4, v98
	v_lshl_add_u32 v99, v94, 2, v95
	v_mul_u32_u24_e32 v185, v99, v97
	v_lshl_add_u32 v185, v96, 3, v185
	v_mov_b32_e32 v97, 160
	v_mul_u32_u24_e32 v184, v99, v97
	v_lshl_add_u32 v184, v96, 3, v184
	s_lshl_b32 s49, s36, 5
	v_add_u32_e32 v184, s49, v184
	v_lshlrev_b32_e32 v188, 4, v94
	v_add_u32_e32 v188, 0x16800, v188
	v_lshrrev_b32_e32 v95, 4, v0
	v_mov_b32_e32 v97, 272
	v_mul_u32_u24_e32 v189, v95, v97
	v_lshl_add_u32 v189, v186, 4, v189
	v_mov_b32_e32 v97, 288
	v_mul_u32_u24_e32 v243, v95, v97
	v_lshl_add_u32 v243, v186, 4, v243
	v_lshrrev_b32_e32 v96, 3, v0
	v_and_b32_e32 v98, 7, v0
	v_mov_b32_e32 v97, 160
	v_mul_u32_u24_e32 v190, v96, v97
	v_lshl_add_u32 v190, v98, 4, v190
	v_add_u32_e32 v191, 0x16800, v194
	s_cmp_gt_u32 s35, 1
	s_cselect_b32 s52, 0x200, 0
	v_add_u32_e32 v191, s52, v191
	s_cmp_eq_u32 s31, 0
	s_cselect_b64 vcc, -1, 0
	v_sub_u32_e32 v99, 63, v95
	v_cndmask_b32_e32 v99, v99, v95, vcc
	v_mul_lo_u32 v244, v99, s30
	v_lshl_add_u32 v244, v186, 4, v244
	v_add_u32_e32 v95, 32, v95
	v_sub_u32_e32 v99, 63, v95
	v_cndmask_b32_e32 v99, v99, v95, vcc
	v_mul_lo_u32 v245, v99, s30
	v_lshl_add_u32 v245, v186, 4, v245
	v_sub_u32_e32 v99, 63, v96
	v_cndmask_b32_e32 v99, v99, v96, vcc
	v_mov_b32_e32 v97, 0x1800
	v_mul_lo_u32 v246, v99, v97
	v_lshl_add_u32 v246, v98, 4, v246
	v_sub_u32_e32 v99, 15, v186
	v_cndmask_b32_e32 v99, v99, v186, vcc
	v_lshlrev_b32_e32 v247, 11, v99
	v_lshl_add_u32 v247, v94, 3, v247
	v_add_u32_e32 v247, s49, v247
	v_lshlrev_b32_e32 v95, 2, v94
	s_lshl_b32 s52, s35, 1
	s_lshr_b32 s75, 0xa90f, s52
	s_and_b32 s75, s75, 3
	s_lshr_b32 s98, 0xa008, s52
	s_and_b32 s98, s98, 3
	s_lshr_b32 s99, 0xa50d, s52
	s_and_b32 s99, s99, 3
	v_cmp_gt_u32_e64 s[92:93], v95, v186
	s_nop 1
	s_cmp_eq_u32 s98, s75
	s_cselect_b64 s[40:41], s[92:93], 0
	s_cmp_eq_u32 s99, s75
	s_cselect_b64 s[80:81], s[92:93], 0
	v_add_u32_e32 v96, 1, v95
	v_cmp_gt_u32_e64 s[92:93], v96, v186
	s_nop 1
	s_cmp_eq_u32 s98, s75
	s_cselect_b64 s[42:43], s[92:93], 0
	s_cmp_eq_u32 s99, s75
	s_cselect_b64 s[82:83], s[92:93], 0
	v_add_u32_e32 v96, 2, v95
	v_cmp_gt_u32_e64 s[92:93], v96, v186
	s_nop 1
	s_cmp_eq_u32 s98, s75
	s_cselect_b64 s[44:45], s[92:93], 0
	s_cmp_eq_u32 s99, s75
	s_cselect_b64 s[84:85], s[92:93], 0
	v_add_u32_e32 v96, 3, v95
	v_cmp_gt_u32_e64 s[92:93], v96, v186
	s_nop 1
	s_cmp_eq_u32 s98, s75
	s_cselect_b64 s[46:47], s[92:93], 0
	s_cmp_eq_u32 s99, s75
	s_cselect_b64 s[86:87], s[92:93], 0
	s_mul_i32 s52, s98, 4608
	v_add_u32_e32 v54, s52, v242
	s_mul_i32 s52, s99, 4608
	v_add_u32_e32 v55, s52, v242
	s_mul_i32 s52, s75, 4352
	v_add_u32_e32 v56, s52, v182
	v_mov_b32_e32 v97, 160
	v_mul_u32_u24_e32 v59, v186, v97
	v_lshl_add_u32 v59, v94, 4, v59
	v_add_u32_e32 v59, 0x17800, v59
	s_mul_i32 s52, s75, 2560
	s_lshr_b32 s53, s98, 1
	s_lshl_b32 s53, s53, 6
	s_add_i32 s53, s53, s52
	s_and_b32 s64, s98, 1
	s_lshl_b32 s64, s64, 3
	s_add_i32 s53, s53, s64
	v_add_u32_e32 v57, s53, v59
	s_lshr_b32 s53, s99, 1
	s_lshl_b32 s53, s53, 6
	s_add_i32 s53, s53, s52
	s_and_b32 s64, s99, 1
	s_lshl_b32 s64, s64, 3
	s_add_i32 s53, s53, s64
	v_add_u32_e32 v58, s53, v59
	v_lshlrev_b32_e32 v96, 4, v0
	v_add_u32_e32 v96, 0x17800, v96
	v_mov_b32_e32 v42, 0
	v_mov_b32_e32 v43, 0
	v_mov_b32_e32 v44, 0
	v_mov_b32_e32 v45, 0
	ds_write_b128 v96, v[42:45]
	ds_write_b128 v96, v[42:45] offset:8192
	v_mov_b32_e32 v2, 0
	v_mov_b32_e32 v3, 0
	v_mov_b32_e32 v4, 0
	v_mov_b32_e32 v5, 0
	v_mov_b32_e32 v6, 0
	v_mov_b32_e32 v7, 0
	v_mov_b32_e32 v8, 0
	v_mov_b32_e32 v9, 0
	v_mov_b32_e32 v10, 0
	v_mov_b32_e32 v11, 0
	v_mov_b32_e32 v12, 0
	v_mov_b32_e32 v13, 0
	v_mov_b32_e32 v14, 0
	v_mov_b32_e32 v15, 0
	v_mov_b32_e32 v16, 0
	v_mov_b32_e32 v17, 0
	v_and_b32_e32 v96, 63, v0
	v_lshlrev_b32_e32 v96, 4, v96
	s_lshl_b32 s52, s36, 1
	s_add_i32 s52, s52, s37
	s_lshl_b32 s53, s52, 11
	s_add_i32 s53, s53, 0x1b800
	v_add_u32_e32 v60, s53, v96
	s_xor_b32 s52, s52, 1
	s_lshl_b32 s53, s52, 11
	s_add_i32 s53, s53, 0x1b800
	v_add_u32_e32 v61, s53, v96
	v_add_u32_e32 v182, 0xb400, v182
	v_add_u32_e32 v183, 0xb400, v183
	v_add_u32_e32 v184, 0xb400, v184
	v_add_u32_e32 v185, 0xb400, v185
	v_add_u32_e32 v242, 0xb400, v242
	v_add_u32_e32 v54, 0xb400, v54
	v_add_u32_e32 v55, 0xb400, v55
	v_add_u32_e32 v56, 0xb400, v56
	v_add_u32_e32 v188, 0x200, v188
	s_mov_b32 s64, 0
	s_min_u32 s65, s64, 35
	s_sub_i32 s48, 3, s65
	s_sub_i32 s49, 39, s65
	s_cmp_lt_u32 s65, 4
	s_cselect_b32 s48, s48, s49
	s_cmp_eq_u32 s31, 0
	s_cselect_b32 s54, s65, s48
	s_lshl_b32 s48, s54, 6
	s_add_i32 s49, s33, s48
	s_add_i32 s48, s34, s48
	s_cmp_lt_u32 s54, 4
	s_cselect_b32 s55, s49, s48
	s_mul_i32 s48, s55, s30
	s_add_u32 s0, s16, s48
	s_addc_u32 s1, s17, 0
	s_add_u32 s2, s18, s48
	s_addc_u32 s3, s19, 0
	s_mul_i32 s48, s55, 0x1800
	s_add_u32 s4, s20, s48
	s_addc_u32 s5, s21, 0
	s_lshl_b32 s48, s54, 9
	s_add_u32 s6, s22, s48
	s_addc_u32 s7, s23, 0
	global_load_dwordx4 v[224:227], v244, s[2:3]
	global_load_dwordx4 v[228:231], v245, s[2:3]
	global_load_dwordx4 v[232:235], v246, s[4:5]
	global_load_dwordx4 v[216:219], v244, s[0:1]
	global_load_dwordx4 v[220:223], v245, s[0:1]
	global_load_dword v236, v194, s[6:7]
	s_mov_b32 s64, 1
	s_min_u32 s65, s64, 35
	s_sub_i32 s48, 3, s65
	s_sub_i32 s49, 39, s65
	s_cmp_lt_u32 s65, 4
	s_cselect_b32 s48, s48, s49
	s_cmp_eq_u32 s31, 0
	s_cselect_b32 s54, s65, s48
	s_lshl_b32 s48, s54, 6
	s_add_i32 s49, s33, s48
	s_add_i32 s48, s34, s48
	s_cmp_lt_u32 s54, 4
	s_cselect_b32 s55, s49, s48
	s_mul_i32 s48, s55, s30
	s_add_u32 s0, s16, s48
	s_addc_u32 s1, s17, 0
	s_add_u32 s2, s18, s48
	s_addc_u32 s3, s19, 0
	s_mul_i32 s48, s55, 0x1800
	s_add_u32 s4, s20, s48
	s_addc_u32 s5, s21, 0
	s_lshl_b32 s48, s54, 9
	s_add_u32 s6, s22, s48
	s_addc_u32 s7, s23, 0
	global_load_dwordx4 v[142:145], v244, s[2:3]
	global_load_dwordx4 v[146:149], v245, s[2:3]
	global_load_dwordx4 v[238:241], v246, s[4:5]
	global_load_dwordx4 v[134:137], v244, s[0:1]
	global_load_dwordx4 v[138:141], v245, s[0:1]
	global_load_dword v237, v194, s[6:7]
	s_waitcnt vmcnt(6)
	ds_write_b128 v243, v[224:227] offset:17408
	ds_write_b128 v243, v[228:231] offset:26624
	ds_write_b128 v190, v[232:235] offset:35840
	ds_write_b128 v189, v[216:219]
	ds_write_b128 v189, v[220:223] offset:8704
	ds_write_b32 v191, v236
	s_mov_b32 s64, 2
	s_min_u32 s65, s64, 35
	s_sub_i32 s48, 3, s65
	s_sub_i32 s49, 39, s65
	s_cmp_lt_u32 s65, 4
	s_cselect_b32 s48, s48, s49
	s_cmp_eq_u32 s31, 0
	s_cselect_b32 s54, s65, s48
	s_lshl_b32 s48, s54, 6
	s_add_i32 s49, s33, s48
	s_add_i32 s48, s34, s48
	s_cmp_lt_u32 s54, 4
	s_cselect_b32 s55, s49, s48
	s_mul_i32 s48, s55, s30
	s_add_u32 s0, s16, s48
	s_addc_u32 s1, s17, 0
	s_add_u32 s2, s18, s48
	s_addc_u32 s3, s19, 0
	s_mul_i32 s48, s55, 0x1800
	s_add_u32 s4, s20, s48
	s_addc_u32 s5, s21, 0
	s_lshl_b32 s48, s54, 9
	s_add_u32 s6, s22, s48
	s_addc_u32 s7, s23, 0
	global_load_dwordx4 v[224:227], v244, s[2:3]
	global_load_dwordx4 v[228:231], v245, s[2:3]
	global_load_dwordx4 v[232:235], v246, s[4:5]
	global_load_dwordx4 v[216:219], v244, s[0:1]
	global_load_dwordx4 v[220:223], v245, s[0:1]
	global_load_dword v236, v194, s[6:7]
	s_mov_b32 s12, 0
	s_waitcnt lgkmcnt(0)
	s_barrier
.Lp8_step:
	v_add_u32_e32 v182, 0xffff4c00, v182
	v_add_u32_e32 v183, 0xffff4c00, v183
	v_add_u32_e32 v184, 0xffff4c00, v184
	v_add_u32_e32 v185, 0xffff4c00, v185
	v_add_u32_e32 v242, 0xffff4c00, v242
	v_add_u32_e32 v54, 0xffff4c00, v54
	v_add_u32_e32 v55, 0xffff4c00, v55
	v_add_u32_e32 v56, 0xffff4c00, v56
	v_add_u32_e32 v189, 0xb400, v189
	v_add_u32_e32 v243, 0xb400, v243
	v_add_u32_e32 v190, 0xb400, v190
	v_add_u32_e32 v188, 0xfffffe00, v188
	v_add_u32_e32 v191, 0x200, v191
	s_cmp_lt_u32 s12, 4
	s_nop 0
	s_cbranch_scc0 .Lp8_lat_0
	s_cmp_eq_u32 s37, 0
	s_cbranch_scc0 .Lp8_ctx1_0
	ds_read_b64_tr_b16 v[126:127], v184 offset:35840
	ds_read_b64_tr_b16 v[128:129], v184 offset:38400
	ds_read_b64_tr_b16 v[130:131], v184 offset:40960
	ds_read_b64_tr_b16 v[132:133], v184 offset:43520
	ds_read_b64_tr_b16 v[62:63], v185 offset:17408
	ds_read_b64_tr_b16 v[64:65], v185 offset:22016
	ds_read_b64_tr_b16 v[66:67], v185 offset:26624
	ds_read_b64_tr_b16 v[68:69], v185 offset:31232
	ds_read_b64_tr_b16 v[70:71], v185 offset:17440
	ds_read_b64_tr_b16 v[72:73], v185 offset:22048
	ds_read_b64_tr_b16 v[74:75], v185 offset:26656
	ds_read_b64_tr_b16 v[76:77], v185 offset:31264
	ds_read_b64_tr_b16 v[78:79], v185 offset:17472
	ds_read_b64_tr_b16 v[80:81], v185 offset:22080
	ds_read_b64_tr_b16 v[82:83], v185 offset:26688
	ds_read_b64_tr_b16 v[84:85], v185 offset:31296
	ds_read_b64_tr_b16 v[86:87], v185 offset:17504
	ds_read_b64_tr_b16 v[88:89], v185 offset:22112
	ds_read_b64_tr_b16 v[90:91], v185 offset:26720
	ds_read_b64_tr_b16 v[92:93], v185 offset:31328
	ds_read_b128 v[166:169], v188 offset:0
	ds_read_b128 v[170:173], v188 offset:64
	ds_read_b128 v[174:177], v188 offset:128
	ds_read_b128 v[178:181], v188 offset:192
	s_waitcnt vmcnt(6)
	ds_write_b128 v243, v[142:145] offset:17408
	ds_write_b128 v243, v[146:149] offset:26624
	ds_write_b128 v190, v[238:241] offset:35840
	ds_write_b128 v189, v[134:137]
	ds_write_b128 v189, v[138:141] offset:8704
	ds_write_b32 v191, v237
	s_add_i32 s64, s12, 3
	s_min_u32 s65, s64, 35
	s_sub_i32 s48, 3, s65
	s_sub_i32 s49, 39, s65
	s_cmp_lt_u32 s65, 4
	s_cselect_b32 s48, s48, s49
	s_cmp_eq_u32 s31, 0
	s_cselect_b32 s54, s65, s48
	s_lshl_b32 s48, s54, 6
	s_add_i32 s49, s33, s48
	s_add_i32 s48, s34, s48
	s_cmp_lt_u32 s54, 4
	s_cselect_b32 s55, s49, s48
	s_mul_i32 s48, s55, s30
	s_add_u32 s0, s16, s48
	s_addc_u32 s1, s17, 0
	s_add_u32 s2, s18, s48
	s_addc_u32 s3, s19, 0
	s_mul_i32 s48, s55, 0x1800
	s_add_u32 s4, s20, s48
	s_addc_u32 s5, s21, 0
	s_lshl_b32 s48, s54, 9
	s_add_u32 s6, s22, s48
	s_addc_u32 s7, s23, 0
	global_load_dwordx4 v[142:145], v244, s[2:3]
	global_load_dwordx4 v[146:149], v245, s[2:3]
	global_load_dwordx4 v[238:241], v246, s[4:5]
	global_load_dwordx4 v[134:137], v244, s[0:1]
	global_load_dwordx4 v[138:141], v245, s[0:1]
	global_load_dword v237, v194, s[6:7]
	s_waitcnt lgkmcnt(10)
	v_mfma_f32_16x16x32_bf16 v[2:5], v[62:65], v[126:129], v[2:5]
	v_mfma_f32_16x16x32_bf16 v[2:5], v[66:69], v[130:133], v[2:5]
	v_mfma_f32_16x16x32_bf16 v[6:9], v[70:73], v[126:129], v[6:9]
	v_mfma_f32_16x16x32_bf16 v[6:9], v[74:77], v[130:133], v[6:9]
	v_mfma_f32_16x16x32_bf16 v[10:13], v[78:81], v[126:129], v[10:13]
	v_mfma_f32_16x16x32_bf16 v[10:13], v[82:85], v[130:133], v[10:13]
	v_mfma_f32_16x16x32_bf16 v[14:17], v[86:89], v[126:129], v[14:17]
	v_mfma_f32_16x16x32_bf16 v[14:17], v[90:93], v[130:133], v[14:17]
	s_waitcnt lgkmcnt(6)
	s_nop 0
	v_pk_mul_f32 v[2:3], v[2:3], v[166:167]
	v_pk_mul_f32 v[4:5], v[4:5], v[168:169]
	v_pk_mul_f32 v[6:7], v[6:7], v[170:171]
	v_pk_mul_f32 v[8:9], v[8:9], v[172:173]
	v_pk_mul_f32 v[10:11], v[10:11], v[174:175]
	v_pk_mul_f32 v[12:13], v[12:13], v[176:177]
	v_pk_mul_f32 v[14:15], v[14:15], v[178:179]
	v_pk_mul_f32 v[16:17], v[16:17], v[180:181]
	v_cvt_pk_bf16_f32 v150, v2, v3
	v_cvt_pk_bf16_f32 v151, v4, v5
	v_cvt_pk_bf16_f32 v152, v6, v7
	v_cvt_pk_bf16_f32 v153, v8, v9
	v_cvt_pk_bf16_f32 v154, v10, v11
	v_cvt_pk_bf16_f32 v155, v12, v13
	v_cvt_pk_bf16_f32 v156, v14, v15
	v_cvt_pk_bf16_f32 v157, v16, v17
	ds_write_b128 v60, v[150:153]
	ds_write_b128 v60, v[154:157] offset:1024
	s_waitcnt lgkmcnt(0)
	s_barrier
	s_branch .Lp8_next_0
.Lp8_ctx1_0:
	ds_read_b64_tr_b16 v[126:127], v184 offset:35840
	ds_read_b64_tr_b16 v[128:129], v184 offset:38400
	ds_read_b64_tr_b16 v[130:131], v184 offset:40960
	ds_read_b64_tr_b16 v[132:133], v184 offset:43520
	ds_read_b64_tr_b16 v[62:63], v185 offset:17536
	ds_read_b64_tr_b16 v[64:65], v185 offset:22144
	ds_read_b64_tr_b16 v[66:67], v185 offset:26752
	ds_read_b64_tr_b16 v[68:69], v185 offset:31360
	ds_read_b64_tr_b16 v[70:71], v185 offset:17568
	ds_read_b64_tr_b16 v[72:73], v185 offset:22176
	ds_read_b64_tr_b16 v[74:75], v185 offset:26784
	ds_read_b64_tr_b16 v[76:77], v185 offset:31392
	ds_read_b64_tr_b16 v[78:79], v185 offset:17600
	ds_read_b64_tr_b16 v[80:81], v185 offset:22208
	ds_read_b64_tr_b16 v[82:83], v185 offset:26816
	ds_read_b64_tr_b16 v[84:85], v185 offset:31424
	ds_read_b64_tr_b16 v[86:87], v185 offset:17632
	ds_read_b64_tr_b16 v[88:89], v185 offset:22240
	ds_read_b64_tr_b16 v[90:91], v185 offset:26848
	ds_read_b64_tr_b16 v[92:93], v185 offset:31456
	ds_read_b128 v[166:169], v188 offset:256
	ds_read_b128 v[170:173], v188 offset:320
	ds_read_b128 v[174:177], v188 offset:384
	ds_read_b128 v[178:181], v188 offset:448
	s_waitcnt vmcnt(6)
	ds_write_b128 v243, v[142:145] offset:17408
	ds_write_b128 v243, v[146:149] offset:26624
	ds_write_b128 v190, v[238:241] offset:35840
	ds_write_b128 v189, v[134:137]
	ds_write_b128 v189, v[138:141] offset:8704
	ds_write_b32 v191, v237
	s_add_i32 s64, s12, 3
	s_min_u32 s65, s64, 35
	s_sub_i32 s48, 3, s65
	s_sub_i32 s49, 39, s65
	s_cmp_lt_u32 s65, 4
	s_cselect_b32 s48, s48, s49
	s_cmp_eq_u32 s31, 0
	s_cselect_b32 s54, s65, s48
	s_lshl_b32 s48, s54, 6
	s_add_i32 s49, s33, s48
	s_add_i32 s48, s34, s48
	s_cmp_lt_u32 s54, 4
	s_cselect_b32 s55, s49, s48
	s_mul_i32 s48, s55, s30
	s_add_u32 s0, s16, s48
	s_addc_u32 s1, s17, 0
	s_add_u32 s2, s18, s48
	s_addc_u32 s3, s19, 0
	s_mul_i32 s48, s55, 0x1800
	s_add_u32 s4, s20, s48
	s_addc_u32 s5, s21, 0
	s_lshl_b32 s48, s54, 9
	s_add_u32 s6, s22, s48
	s_addc_u32 s7, s23, 0
	global_load_dwordx4 v[142:145], v244, s[2:3]
	global_load_dwordx4 v[146:149], v245, s[2:3]
	global_load_dwordx4 v[238:241], v246, s[4:5]
	global_load_dwordx4 v[134:137], v244, s[0:1]
	global_load_dwordx4 v[138:141], v245, s[0:1]
	global_load_dword v237, v194, s[6:7]
	s_waitcnt lgkmcnt(10)
	v_mfma_f32_16x16x32_bf16 v[2:5], v[62:65], v[126:129], v[2:5]
	v_mfma_f32_16x16x32_bf16 v[2:5], v[66:69], v[130:133], v[2:5]
	v_mfma_f32_16x16x32_bf16 v[6:9], v[70:73], v[126:129], v[6:9]
	v_mfma_f32_16x16x32_bf16 v[6:9], v[74:77], v[130:133], v[6:9]
	v_mfma_f32_16x16x32_bf16 v[10:13], v[78:81], v[126:129], v[10:13]
	v_mfma_f32_16x16x32_bf16 v[10:13], v[82:85], v[130:133], v[10:13]
	v_mfma_f32_16x16x32_bf16 v[14:17], v[86:89], v[126:129], v[14:17]
	v_mfma_f32_16x16x32_bf16 v[14:17], v[90:93], v[130:133], v[14:17]
	s_waitcnt lgkmcnt(6)
	s_nop 0
	v_pk_mul_f32 v[2:3], v[2:3], v[166:167]
	v_pk_mul_f32 v[4:5], v[4:5], v[168:169]
	v_pk_mul_f32 v[6:7], v[6:7], v[170:171]
	v_pk_mul_f32 v[8:9], v[8:9], v[172:173]
	v_pk_mul_f32 v[10:11], v[10:11], v[174:175]
	v_pk_mul_f32 v[12:13], v[12:13], v[176:177]
	v_pk_mul_f32 v[14:15], v[14:15], v[178:179]
	v_pk_mul_f32 v[16:17], v[16:17], v[180:181]
	v_cvt_pk_bf16_f32 v158, v2, v3
	v_cvt_pk_bf16_f32 v159, v4, v5
	v_cvt_pk_bf16_f32 v160, v6, v7
	v_cvt_pk_bf16_f32 v161, v8, v9
	v_cvt_pk_bf16_f32 v162, v10, v11
	v_cvt_pk_bf16_f32 v163, v12, v13
	v_cvt_pk_bf16_f32 v164, v14, v15
	v_cvt_pk_bf16_f32 v165, v16, v17
	ds_write_b128 v60, v[158:161]
	ds_write_b128 v60, v[162:165] offset:1024
	s_waitcnt lgkmcnt(0)
	s_barrier
	s_branch .Lp8_next_0
.Lp8_lat_0:
	s_cmp_eq_u32 s37, 0
	s_cbranch_scc0 .Lp8_lat1_0
	s_sub_i32 s48, 3, s12
	s_sub_i32 s49, 39, s12
	s_cmp_lt_u32 s12, 4
	s_cselect_b32 s48, s48, s49
	s_cmp_eq_u32 s31, 0
	s_cselect_b32 s54, s12, s48
	s_lshl_b32 s48, s54, 6
	s_add_i32 s49, s33, s48
	s_add_i32 s48, s34, s48
	s_cmp_lt_u32 s54, 4
	s_cselect_b32 s55, s49, s48
	s_add_i32 s48, s55, 0
	s_add_i32 s49, s55, 48
	s_cmp_eq_u32 s31, 0
	s_cselect_b32 s48, s48, s49
	s_lshl_b32 s48, s48, 11
	s_add_u32 s8, s28, s48
	s_addc_u32 s9, s29, 0
	s_add_i32 s48, s55, 48
	s_add_i32 s49, s55, 0
	s_cmp_eq_u32 s31, 0
	s_cselect_b32 s48, s48, s49
	s_lshl_b32 s48, s48, 11
	s_add_u32 s10, s28, s48
	s_addc_u32 s11, s29, 0
	ds_read_b64_tr_b16 v[126:127], v184 offset:35840
	ds_read_b64_tr_b16 v[128:129], v184 offset:38400
	ds_read_b64_tr_b16 v[130:131], v184 offset:40960
	ds_read_b64_tr_b16 v[132:133], v184 offset:43520
	ds_read_b64_tr_b16 v[62:63], v185 offset:17408
	ds_read_b64_tr_b16 v[64:65], v185 offset:22016
	ds_read_b64_tr_b16 v[66:67], v185 offset:26624
	ds_read_b64_tr_b16 v[68:69], v185 offset:31232
	ds_read_b64_tr_b16 v[70:71], v185 offset:17440
	ds_read_b64_tr_b16 v[72:73], v185 offset:22048
	ds_read_b64_tr_b16 v[74:75], v185 offset:26656
	ds_read_b64_tr_b16 v[76:77], v185 offset:31264
	ds_read_b64_tr_b16 v[78:79], v185 offset:17472
	ds_read_b64_tr_b16 v[80:81], v185 offset:22080
	ds_read_b64_tr_b16 v[82:83], v185 offset:26688
	ds_read_b64_tr_b16 v[84:85], v185 offset:31296
	ds_read_b64_tr_b16 v[86:87], v185 offset:17504
	ds_read_b64_tr_b16 v[88:89], v185 offset:22112
	ds_read_b64_tr_b16 v[90:91], v185 offset:26720
	ds_read_b64_tr_b16 v[92:93], v185 offset:31328
	s_waitcnt lgkmcnt(0)
	v_mfma_f32_16x16x32_bf16 v[2:5], v[62:65], v[126:129], v[2:5]
	v_mfma_f32_16x16x32_bf16 v[2:5], v[66:69], v[130:133], v[2:5]
	v_mfma_f32_16x16x32_bf16 v[6:9], v[70:73], v[126:129], v[6:9]
	v_mfma_f32_16x16x32_bf16 v[6:9], v[74:77], v[130:133], v[6:9]
	v_mfma_f32_16x16x32_bf16 v[10:13], v[78:81], v[126:129], v[10:13]
	v_mfma_f32_16x16x32_bf16 v[10:13], v[82:85], v[130:133], v[10:13]
	v_mfma_f32_16x16x32_bf16 v[14:17], v[86:89], v[126:129], v[14:17]
	v_mfma_f32_16x16x32_bf16 v[14:17], v[90:93], v[130:133], v[14:17]
	ds_read_b128 v[62:65], v56 offset:0
	ds_read_b128 v[66:69], v56 offset:64
	ds_read_b128 v[70:73], v56 offset:128
	ds_read_b128 v[74:77], v56 offset:192
	ds_read_b128 v[166:169], v54 offset:17408
	ds_read_b128 v[170:173], v54 offset:17472
	ds_read_b128 v[174:177], v54 offset:17536
	ds_read_b128 v[178:181], v54 offset:17600
	ds_read_b128 v[200:203], v55 offset:17408
	ds_read_b128 v[204:207], v55 offset:17472
	ds_read_b128 v[208:211], v55 offset:17536
	ds_read_b128 v[212:215], v55 offset:17600
	ds_read_b64 v[94:95], v183 offset:0
	ds_read_b64 v[96:97], v183 offset:32
	ds_read_b64 v[98:99], v183 offset:64
	ds_read_b64 v[100:101], v183 offset:96
	ds_read_b64 v[102:103], v183 offset:128
	ds_read_b64 v[104:105], v183 offset:160
	ds_read_b64 v[106:107], v183 offset:192
	ds_read_b64 v[108:109], v183 offset:224
	ds_read_b64 v[110:111], v183 offset:13056
	ds_read_b64 v[112:113], v183 offset:13088
	ds_read_b64 v[114:115], v183 offset:13120
	ds_read_b64 v[116:117], v183 offset:13152
	ds_read_b64 v[118:119], v183 offset:13184
	ds_read_b64 v[120:121], v183 offset:13216
	ds_read_b64 v[122:123], v183 offset:13248
	ds_read_b64 v[124:125], v183 offset:13280
	s_cmp_gt_u32 s12, 5
	s_cbranch_scc1 .Lp8_w10_3
	s_waitcnt vmcnt(6)
	s_branch .Lp8_wd_3

.Lp8_wd_3:
	ds_write_b128 v243, v[142:145] offset:17408
	ds_write_b128 v243, v[146:149] offset:26624
	ds_write_b128 v190, v[238:241] offset:35840
	ds_write_b128 v189, v[134:137]
	ds_write_b128 v189, v[138:141] offset:8704
	ds_write_b32 v191, v237
	s_add_i32 s64, s12, 3
	s_min_u32 s65, s64, 35
	s_sub_i32 s48, 3, s65
	s_sub_i32 s49, 39, s65
	s_cmp_lt_u32 s65, 4
	s_cselect_b32 s48, s48, s49
	s_cmp_eq_u32 s31, 0
	s_cselect_b32 s54, s65, s48
	s_lshl_b32 s48, s54, 6
	s_add_i32 s49, s33, s48
	s_add_i32 s48, s34, s48
	s_cmp_lt_u32 s54, 4
	s_cselect_b32 s55, s49, s48
	s_mul_i32 s48, s55, s30
	s_add_u32 s0, s16, s48
	s_addc_u32 s1, s17, 0
	s_add_u32 s2, s18, s48
	s_addc_u32 s3, s19, 0
	s_mul_i32 s48, s55, 0x1800
	s_add_u32 s4, s20, s48
	s_addc_u32 s5, s21, 0
	s_lshl_b32 s48, s54, 9
	s_add_u32 s6, s22, s48
	s_addc_u32 s7, s23, 0
	global_load_dwordx4 v[142:145], v244, s[2:3]
	global_load_dwordx4 v[146:149], v245, s[2:3]
	global_load_dwordx4 v[238:241], v246, s[4:5]
	global_load_dwordx4 v[134:137], v244, s[0:1]
	global_load_dwordx4 v[138:141], v245, s[0:1]
	global_load_dword v237, v194, s[6:7]
	s_waitcnt lgkmcnt(15)
	v_mfma_f32_16x16x32_bf16 v[42:45], v[166:169], v[62:65], 0
	v_mfma_f32_16x16x32_bf16 v[46:49], v[200:203], v[62:65], 0
	v_mfma_f32_16x16x32_bf16 v[42:45], v[170:173], v[66:69], v[42:45]
	v_mfma_f32_16x16x32_bf16 v[46:49], v[204:207], v[66:69], v[46:49]
	v_mfma_f32_16x16x32_bf16 v[42:45], v[174:177], v[70:73], v[42:45]
	v_mfma_f32_16x16x32_bf16 v[46:49], v[208:211], v[70:73], v[46:49]
	v_mfma_f32_16x16x32_bf16 v[42:45], v[178:181], v[74:77], v[42:45]
	v_mfma_f32_16x16x32_bf16 v[46:49], v[212:215], v[74:77], v[46:49]
	s_nop 6
	v_cndmask_b32_e64 v42, v42, 0, s[40:41]
	v_cndmask_b32_e64 v43, v43, 0, s[42:43]
	v_cndmask_b32_e64 v44, v44, 0, s[44:45]
	v_cndmask_b32_e64 v45, v45, 0, s[46:47]
	v_cndmask_b32_e64 v46, v46, 0, s[80:81]
	v_cndmask_b32_e64 v47, v47, 0, s[82:83]
	v_cndmask_b32_e64 v48, v48, 0, s[84:85]
	v_cndmask_b32_e64 v49, v49, 0, s[86:87]
	v_cvt_pk_bf16_f32 v50, v42, v43
	v_cvt_pk_bf16_f32 v51, v44, v45
	v_cvt_pk_bf16_f32 v52, v46, v47
	v_cvt_pk_bf16_f32 v53, v48, v49
	ds_write_b64 v57, v[50:51]
	ds_write_b64 v58, v[52:53]
	s_waitcnt lgkmcnt(0)
	s_barrier
	ds_read_b128 v[158:161], v61
	ds_read_b128 v[162:165], v61 offset:1024
	ds_read_b128 v[18:21], v59 offset:0
	ds_read_b128 v[22:25], v59 offset:7680
	ds_read_b128 v[26:29], v59 offset:7744
	ds_read_b128 v[166:169], v188 offset:0
	ds_read_b128 v[170:173], v188 offset:64
	ds_read_b128 v[174:177], v188 offset:128
	ds_read_b128 v[178:181], v188 offset:192
	s_waitcnt lgkmcnt(7)
	v_mfma_f32_16x16x32_bf16 v[34:37], v[150:153], v[94:97], 0
	v_mfma_f32_16x16x32_bf16 v[38:41], v[150:153], v[110:113], 0
	v_mfma_f32_16x16x32_bf16 v[34:37], v[154:157], v[98:101], v[34:37]
	v_mfma_f32_16x16x32_bf16 v[38:41], v[154:157], v[114:117], v[38:41]
	v_mfma_f32_16x16x32_bf16 v[34:37], v[158:161], v[102:105], v[34:37]
	v_mfma_f32_16x16x32_bf16 v[38:41], v[158:161], v[118:121], v[38:41]
	v_mfma_f32_16x16x32_bf16 v[34:37], v[162:165], v[106:109], v[34:37]
	v_mfma_f32_16x16x32_bf16 v[38:41], v[162:165], v[122:125], v[38:41]
	s_waitcnt lgkmcnt(4)
	v_mfma_f32_16x16x32_bf16 v[34:37], v[126:129], v[18:21], v[34:37]
	v_mfma_f32_16x16x32_bf16 v[38:41], v[126:129], v[22:25], v[38:41]
	v_mfma_f32_16x16x32_bf16 v[38:41], v[130:133], v[26:29], v[38:41]
	s_waitcnt lgkmcnt(0)
	s_nop 4
	v_cvt_pk_bf16_f32 v50, v34, v35
	v_cvt_pk_bf16_f32 v51, v36, v37
	global_store_dwordx2 v247, v[50:51], s[8:9]
	v_cvt_pk_bf16_f32 v52, v38, v39
	v_cvt_pk_bf16_f32 v53, v40, v41
	global_store_dwordx2 v247, v[52:53], s[10:11]
	v_pk_mul_f32 v[2:3], v[2:3], v[166:167]
	v_pk_mul_f32 v[4:5], v[4:5], v[168:169]
	v_pk_mul_f32 v[6:7], v[6:7], v[170:171]
	v_pk_mul_f32 v[8:9], v[8:9], v[172:173]
	v_pk_mul_f32 v[10:11], v[10:11], v[174:175]
	v_pk_mul_f32 v[12:13], v[12:13], v[176:177]
	v_pk_mul_f32 v[14:15], v[14:15], v[178:179]
	v_pk_mul_f32 v[16:17], v[16:17], v[180:181]
	v_cvt_pk_bf16_f32 v150, v2, v3
	v_cvt_pk_bf16_f32 v151, v4, v5
	v_cvt_pk_bf16_f32 v152, v6, v7
	v_cvt_pk_bf16_f32 v153, v8, v9
	v_cvt_pk_bf16_f32 v154, v10, v11
	v_cvt_pk_bf16_f32 v155, v12, v13
	v_cvt_pk_bf16_f32 v156, v14, v15
	v_cvt_pk_bf16_f32 v157, v16, v17
	ds_write_b128 v60, v[150:153]
	ds_write_b128 v60, v[154:157] offset:1024
	s_waitcnt lgkmcnt(0)
	s_barrier
	s_branch .Lp8_next_0
.Lp8_lat1_0:
	s_cmp_eq_u32 s12, 4
	s_cbranch_scc1 .Lp8_first_4
	ds_read_b128 v[18:21], v59 offset:2560
	ds_read_b128 v[22:25], v59 offset:5120
	ds_read_b128 v[26:29], v59 offset:5184
	s_waitcnt lgkmcnt(0)
	v_mfma_f32_16x16x32_bf16 v[34:37], v[126:129], v[18:21], v[34:37]
	v_mfma_f32_16x16x32_bf16 v[38:41], v[126:129], v[22:25], v[38:41]
	v_mfma_f32_16x16x32_bf16 v[38:41], v[130:133], v[26:29], v[38:41]
	s_nop 5
	v_cvt_pk_bf16_f32 v50, v34, v35
	v_cvt_pk_bf16_f32 v51, v36, v37
	global_store_dwordx2 v247, v[50:51], s[76:77]
	v_cvt_pk_bf16_f32 v52, v38, v39
	v_cvt_pk_bf16_f32 v53, v40, v41
	global_store_dwordx2 v247, v[52:53], s[78:79]
	v_pk_mul_f32 v[2:3], v[2:3], v[166:167]
	v_pk_mul_f32 v[4:5], v[4:5], v[168:169]
	v_pk_mul_f32 v[6:7], v[6:7], v[170:171]
	v_pk_mul_f32 v[8:9], v[8:9], v[172:173]
	v_pk_mul_f32 v[10:11], v[10:11], v[174:175]
	v_pk_mul_f32 v[12:13], v[12:13], v[176:177]
	v_pk_mul_f32 v[14:15], v[14:15], v[178:179]
	v_pk_mul_f32 v[16:17], v[16:17], v[180:181]
	v_cvt_pk_bf16_f32 v158, v2, v3
	v_cvt_pk_bf16_f32 v159, v4, v5
	v_cvt_pk_bf16_f32 v160, v6, v7
	v_cvt_pk_bf16_f32 v161, v8, v9
	v_cvt_pk_bf16_f32 v162, v10, v11
	v_cvt_pk_bf16_f32 v163, v12, v13
	v_cvt_pk_bf16_f32 v164, v14, v15
	v_cvt_pk_bf16_f32 v165, v16, v17
	ds_write_b128 v60, v[158:161]
	ds_write_b128 v60, v[162:165] offset:1024
.Lp8_first_4:
	s_sub_i32 s48, 3, s12
	s_sub_i32 s49, 39, s12
	s_cmp_lt_u32 s12, 4
	s_cselect_b32 s48, s48, s49
	s_cmp_eq_u32 s31, 0
	s_cselect_b32 s54, s12, s48
	s_lshl_b32 s48, s54, 6
	s_add_i32 s49, s33, s48
	s_add_i32 s48, s34, s48
	s_cmp_lt_u32 s54, 4
	s_cselect_b32 s55, s49, s48
	s_add_i32 s48, s55, 16
	s_add_i32 s49, s55, 32
	s_cmp_eq_u32 s31, 0
	s_cselect_b32 s48, s48, s49
	s_lshl_b32 s48, s48, 11
	s_add_u32 s8, s28, s48
	s_addc_u32 s9, s29, 0
	s_add_i32 s48, s55, 32
	s_add_i32 s49, s55, 16
	s_cmp_eq_u32 s31, 0
	s_cselect_b32 s48, s48, s49
	s_lshl_b32 s48, s48, 11
	s_add_u32 s10, s28, s48
	s_addc_u32 s11, s29, 0
	ds_read_b64_tr_b16 v[126:127], v184 offset:35840
	ds_read_b64_tr_b16 v[128:129], v184 offset:38400
	ds_read_b64_tr_b16 v[130:131], v184 offset:40960
	ds_read_b64_tr_b16 v[132:133], v184 offset:43520
	ds_read_b64_tr_b16 v[62:63], v185 offset:17536
	ds_read_b64_tr_b16 v[64:65], v185 offset:22144
	ds_read_b64_tr_b16 v[66:67], v185 offset:26752
	ds_read_b64_tr_b16 v[68:69], v185 offset:31360
	ds_read_b64_tr_b16 v[70:71], v185 offset:17568
	ds_read_b64_tr_b16 v[72:73], v185 offset:22176
	ds_read_b64_tr_b16 v[74:75], v185 offset:26784
	ds_read_b64_tr_b16 v[76:77], v185 offset:31392
	ds_read_b64_tr_b16 v[78:79], v185 offset:17600
	ds_read_b64_tr_b16 v[80:81], v185 offset:22208
	ds_read_b64_tr_b16 v[82:83], v185 offset:26816
	ds_read_b64_tr_b16 v[84:85], v185 offset:31424
	ds_read_b64_tr_b16 v[86:87], v185 offset:17632
	ds_read_b64_tr_b16 v[88:89], v185 offset:22240
	ds_read_b64_tr_b16 v[90:91], v185 offset:26848
	ds_read_b64_tr_b16 v[92:93], v185 offset:31456
	ds_read_b64 v[94:95], v183 offset:4352
	ds_read_b64 v[96:97], v183 offset:4384
	ds_read_b64 v[98:99], v183 offset:4416
	ds_read_b64 v[100:101], v183 offset:4448
	ds_read_b64 v[102:103], v183 offset:4480
	ds_read_b64 v[104:105], v183 offset:4512
	ds_read_b64 v[106:107], v183 offset:4544
	ds_read_b64 v[108:109], v183 offset:4576
	ds_read_b64 v[110:111], v183 offset:8704
	ds_read_b64 v[112:113], v183 offset:8736
	ds_read_b64 v[114:115], v183 offset:8768
	ds_read_b64 v[116:117], v183 offset:8800
	ds_read_b64 v[118:119], v183 offset:8832
	ds_read_b64 v[120:121], v183 offset:8864
	ds_read_b64 v[122:123], v183 offset:8896
	ds_read_b64 v[124:125], v183 offset:8928
	ds_read_b128 v[150:153], v61
	ds_read_b128 v[154:157], v61 offset:1024
	s_waitcnt lgkmcnt(15)
	v_mfma_f32_16x16x32_bf16 v[2:5], v[62:65], v[126:129], v[2:5]
	v_mfma_f32_16x16x32_bf16 v[2:5], v[66:69], v[130:133], v[2:5]
	v_mfma_f32_16x16x32_bf16 v[6:9], v[70:73], v[126:129], v[6:9]
	v_mfma_f32_16x16x32_bf16 v[6:9], v[74:77], v[130:133], v[6:9]
	v_mfma_f32_16x16x32_bf16 v[10:13], v[78:81], v[126:129], v[10:13]
	v_mfma_f32_16x16x32_bf16 v[10:13], v[82:85], v[130:133], v[10:13]
	v_mfma_f32_16x16x32_bf16 v[14:17], v[86:89], v[126:129], v[14:17]
	v_mfma_f32_16x16x32_bf16 v[14:17], v[90:93], v[130:133], v[14:17]
	s_waitcnt lgkmcnt(0)
	v_mfma_f32_16x16x32_bf16 v[34:37], v[150:153], v[94:97], 0
	v_mfma_f32_16x16x32_bf16 v[38:41], v[150:153], v[110:113], 0
	v_mfma_f32_16x16x32_bf16 v[34:37], v[154:157], v[98:101], v[34:37]
	v_mfma_f32_16x16x32_bf16 v[38:41], v[154:157], v[114:117], v[38:41]
	v_mfma_f32_16x16x32_bf16 v[34:37], v[158:161], v[102:105], v[34:37]
	v_mfma_f32_16x16x32_bf16 v[38:41], v[158:161], v[118:121], v[38:41]
	v_mfma_f32_16x16x32_bf16 v[34:37], v[162:165], v[106:109], v[34:37]
	v_mfma_f32_16x16x32_bf16 v[38:41], v[162:165], v[122:125], v[38:41]
	ds_read_b128 v[62:65], v56 offset:0
	ds_read_b128 v[66:69], v56 offset:64
	ds_read_b128 v[70:73], v56 offset:128
	ds_read_b128 v[74:77], v56 offset:192
	ds_read_b128 v[166:169], v54 offset:17408
	ds_read_b128 v[170:173], v54 offset:17472
	ds_read_b128 v[174:177], v54 offset:17536
	ds_read_b128 v[178:181], v54 offset:17600
	ds_read_b128 v[200:203], v55 offset:17408
	ds_read_b128 v[204:207], v55 offset:17472
	ds_read_b128 v[208:211], v55 offset:17536
	ds_read_b128 v[212:215], v55 offset:17600
	s_cmp_gt_u32 s12, 5
	s_cbranch_scc1 .Lp8_w10_5
	s_waitcnt vmcnt(6)
	s_branch .Lp8_wd_5

.Lp8_wd_5:
	ds_write_b128 v243, v[142:145] offset:17408
	ds_write_b128 v243, v[146:149] offset:26624
	ds_write_b128 v190, v[238:241] offset:35840
	ds_write_b128 v189, v[134:137]
	ds_write_b128 v189, v[138:141] offset:8704
	ds_write_b32 v191, v237
	s_add_i32 s64, s12, 3
	s_min_u32 s65, s64, 35
	s_sub_i32 s48, 3, s65
	s_sub_i32 s49, 39, s65
	s_cmp_lt_u32 s65, 4
	s_cselect_b32 s48, s48, s49
	s_cmp_eq_u32 s31, 0
	s_cselect_b32 s54, s65, s48
	s_lshl_b32 s48, s54, 6
	s_add_i32 s49, s33, s48
	s_add_i32 s48, s34, s48
	s_cmp_lt_u32 s54, 4
	s_cselect_b32 s55, s49, s48
	s_mul_i32 s48, s55, s30
	s_add_u32 s0, s16, s48
	s_addc_u32 s1, s17, 0
	s_add_u32 s2, s18, s48
	s_addc_u32 s3, s19, 0
	s_mul_i32 s48, s55, 0x1800
	s_add_u32 s4, s20, s48
	s_addc_u32 s5, s21, 0
	s_lshl_b32 s48, s54, 9
	s_add_u32 s6, s22, s48
	s_addc_u32 s7, s23, 0
	global_load_dwordx4 v[142:145], v244, s[2:3]
	global_load_dwordx4 v[146:149], v245, s[2:3]
	global_load_dwordx4 v[238:241], v246, s[4:5]
	global_load_dwordx4 v[134:137], v244, s[0:1]
	global_load_dwordx4 v[138:141], v245, s[0:1]
	global_load_dword v237, v194, s[6:7]
	s_waitcnt lgkmcnt(0)
	s_barrier
	v_mfma_f32_16x16x32_bf16 v[42:45], v[166:169], v[62:65], 0
	v_mfma_f32_16x16x32_bf16 v[46:49], v[200:203], v[62:65], 0
	v_mfma_f32_16x16x32_bf16 v[42:45], v[170:173], v[66:69], v[42:45]
	v_mfma_f32_16x16x32_bf16 v[46:49], v[204:207], v[66:69], v[46:49]
	v_mfma_f32_16x16x32_bf16 v[42:45], v[174:177], v[70:73], v[42:45]
	v_mfma_f32_16x16x32_bf16 v[46:49], v[208:211], v[70:73], v[46:49]
	v_mfma_f32_16x16x32_bf16 v[42:45], v[178:181], v[74:77], v[42:45]
	v_mfma_f32_16x16x32_bf16 v[46:49], v[212:215], v[74:77], v[46:49]
	s_nop 6
	v_cndmask_b32_e64 v42, v42, 0, s[40:41]
	v_cndmask_b32_e64 v43, v43, 0, s[42:43]
	v_cndmask_b32_e64 v44, v44, 0, s[44:45]
	v_cndmask_b32_e64 v45, v45, 0, s[46:47]
	v_cndmask_b32_e64 v46, v46, 0, s[80:81]
	v_cndmask_b32_e64 v47, v47, 0, s[82:83]
	v_cndmask_b32_e64 v48, v48, 0, s[84:85]
	v_cndmask_b32_e64 v49, v49, 0, s[86:87]
	v_cvt_pk_bf16_f32 v50, v42, v43
	v_cvt_pk_bf16_f32 v51, v44, v45
	v_cvt_pk_bf16_f32 v52, v46, v47
	v_cvt_pk_bf16_f32 v53, v48, v49
	ds_write_b64 v57, v[50:51]
	ds_write_b64 v58, v[52:53]
	ds_read_b128 v[166:169], v188 offset:256
	ds_read_b128 v[170:173], v188 offset:320
	ds_read_b128 v[174:177], v188 offset:384
	ds_read_b128 v[178:181], v188 offset:448
	s_mov_b64 s[76:77], s[8:9]
	s_mov_b64 s[78:79], s[10:11]
	s_waitcnt lgkmcnt(4)
	s_barrier
.Lp8_next_0:
	s_add_i32 s12, s12, 1
	v_add_u32_e32 v182, 0xb400, v182
	v_add_u32_e32 v183, 0xb400, v183
	v_add_u32_e32 v184, 0xb400, v184
	v_add_u32_e32 v185, 0xb400, v185
	v_add_u32_e32 v242, 0xb400, v242
	v_add_u32_e32 v54, 0xb400, v54
	v_add_u32_e32 v55, 0xb400, v55
	v_add_u32_e32 v56, 0xb400, v56
	v_add_u32_e32 v189, 0xffff4c00, v189
	v_add_u32_e32 v243, 0xffff4c00, v243
	v_add_u32_e32 v190, 0xffff4c00, v190
	v_add_u32_e32 v188, 0x200, v188
	v_add_u32_e32 v191, 0xfffffe00, v191
	s_cmp_lt_u32 s12, 4
	s_nop 0
	s_cbranch_scc0 .Lp8_lat_1
	s_cmp_eq_u32 s37, 0
	s_cbranch_scc0 .Lp8_ctx1_1
	ds_read_b64_tr_b16 v[126:127], v184 offset:35840
	ds_read_b64_tr_b16 v[128:129], v184 offset:38400
	ds_read_b64_tr_b16 v[130:131], v184 offset:40960
	ds_read_b64_tr_b16 v[132:133], v184 offset:43520
	ds_read_b64_tr_b16 v[62:63], v185 offset:17408
	ds_read_b64_tr_b16 v[64:65], v185 offset:22016
	ds_read_b64_tr_b16 v[66:67], v185 offset:26624
	ds_read_b64_tr_b16 v[68:69], v185 offset:31232
	ds_read_b64_tr_b16 v[70:71], v185 offset:17440
	ds_read_b64_tr_b16 v[72:73], v185 offset:22048
	ds_read_b64_tr_b16 v[74:75], v185 offset:26656
	ds_read_b64_tr_b16 v[76:77], v185 offset:31264
	ds_read_b64_tr_b16 v[78:79], v185 offset:17472
	ds_read_b64_tr_b16 v[80:81], v185 offset:22080
	ds_read_b64_tr_b16 v[82:83], v185 offset:26688
	ds_read_b64_tr_b16 v[84:85], v185 offset:31296
	ds_read_b64_tr_b16 v[86:87], v185 offset:17504
	ds_read_b64_tr_b16 v[88:89], v185 offset:22112
	ds_read_b64_tr_b16 v[90:91], v185 offset:26720
	ds_read_b64_tr_b16 v[92:93], v185 offset:31328
	ds_read_b128 v[166:169], v188 offset:0
	ds_read_b128 v[170:173], v188 offset:64
	ds_read_b128 v[174:177], v188 offset:128
	ds_read_b128 v[178:181], v188 offset:192
	s_waitcnt vmcnt(6)
	ds_write_b128 v243, v[224:227] offset:17408
	ds_write_b128 v243, v[228:231] offset:26624
	ds_write_b128 v190, v[232:235] offset:35840
	ds_write_b128 v189, v[216:219]
	ds_write_b128 v189, v[220:223] offset:8704
	ds_write_b32 v191, v236
	s_add_i32 s64, s12, 3
	s_min_u32 s65, s64, 35
	s_sub_i32 s48, 3, s65
	s_sub_i32 s49, 39, s65
	s_cmp_lt_u32 s65, 4
	s_cselect_b32 s48, s48, s49
	s_cmp_eq_u32 s31, 0
	s_cselect_b32 s54, s65, s48
	s_lshl_b32 s48, s54, 6
	s_add_i32 s49, s33, s48
	s_add_i32 s48, s34, s48
	s_cmp_lt_u32 s54, 4
	s_cselect_b32 s55, s49, s48
	s_mul_i32 s48, s55, s30
	s_add_u32 s0, s16, s48
	s_addc_u32 s1, s17, 0
	s_add_u32 s2, s18, s48
	s_addc_u32 s3, s19, 0
	s_mul_i32 s48, s55, 0x1800
	s_add_u32 s4, s20, s48
	s_addc_u32 s5, s21, 0
	s_lshl_b32 s48, s54, 9
	s_add_u32 s6, s22, s48
	s_addc_u32 s7, s23, 0
	global_load_dwordx4 v[224:227], v244, s[2:3]
	global_load_dwordx4 v[228:231], v245, s[2:3]
	global_load_dwordx4 v[232:235], v246, s[4:5]
	global_load_dwordx4 v[216:219], v244, s[0:1]
	global_load_dwordx4 v[220:223], v245, s[0:1]
	global_load_dword v236, v194, s[6:7]
	s_waitcnt lgkmcnt(10)
	v_mfma_f32_16x16x32_bf16 v[2:5], v[62:65], v[126:129], v[2:5]
	v_mfma_f32_16x16x32_bf16 v[2:5], v[66:69], v[130:133], v[2:5]
	v_mfma_f32_16x16x32_bf16 v[6:9], v[70:73], v[126:129], v[6:9]
	v_mfma_f32_16x16x32_bf16 v[6:9], v[74:77], v[130:133], v[6:9]
	v_mfma_f32_16x16x32_bf16 v[10:13], v[78:81], v[126:129], v[10:13]
	v_mfma_f32_16x16x32_bf16 v[10:13], v[82:85], v[130:133], v[10:13]
	v_mfma_f32_16x16x32_bf16 v[14:17], v[86:89], v[126:129], v[14:17]
	v_mfma_f32_16x16x32_bf16 v[14:17], v[90:93], v[130:133], v[14:17]
	s_waitcnt lgkmcnt(6)
	s_nop 0
	v_pk_mul_f32 v[2:3], v[2:3], v[166:167]
	v_pk_mul_f32 v[4:5], v[4:5], v[168:169]
	v_pk_mul_f32 v[6:7], v[6:7], v[170:171]
	v_pk_mul_f32 v[8:9], v[8:9], v[172:173]
	v_pk_mul_f32 v[10:11], v[10:11], v[174:175]
	v_pk_mul_f32 v[12:13], v[12:13], v[176:177]
	v_pk_mul_f32 v[14:15], v[14:15], v[178:179]
	v_pk_mul_f32 v[16:17], v[16:17], v[180:181]
	v_cvt_pk_bf16_f32 v150, v2, v3
	v_cvt_pk_bf16_f32 v151, v4, v5
	v_cvt_pk_bf16_f32 v152, v6, v7
	v_cvt_pk_bf16_f32 v153, v8, v9
	v_cvt_pk_bf16_f32 v154, v10, v11
	v_cvt_pk_bf16_f32 v155, v12, v13
	v_cvt_pk_bf16_f32 v156, v14, v15
	v_cvt_pk_bf16_f32 v157, v16, v17
	ds_write_b128 v60, v[150:153]
	ds_write_b128 v60, v[154:157] offset:1024
	s_waitcnt lgkmcnt(0)
	s_barrier
	s_branch .Lp8_next_1
.Lp8_ctx1_1:
	ds_read_b64_tr_b16 v[126:127], v184 offset:35840
	ds_read_b64_tr_b16 v[128:129], v184 offset:38400
	ds_read_b64_tr_b16 v[130:131], v184 offset:40960
	ds_read_b64_tr_b16 v[132:133], v184 offset:43520
	ds_read_b64_tr_b16 v[62:63], v185 offset:17536
	ds_read_b64_tr_b16 v[64:65], v185 offset:22144
	ds_read_b64_tr_b16 v[66:67], v185 offset:26752
	ds_read_b64_tr_b16 v[68:69], v185 offset:31360
	ds_read_b64_tr_b16 v[70:71], v185 offset:17568
	ds_read_b64_tr_b16 v[72:73], v185 offset:22176
	ds_read_b64_tr_b16 v[74:75], v185 offset:26784
	ds_read_b64_tr_b16 v[76:77], v185 offset:31392
	ds_read_b64_tr_b16 v[78:79], v185 offset:17600
	ds_read_b64_tr_b16 v[80:81], v185 offset:22208
	ds_read_b64_tr_b16 v[82:83], v185 offset:26816
	ds_read_b64_tr_b16 v[84:85], v185 offset:31424
	ds_read_b64_tr_b16 v[86:87], v185 offset:17632
	ds_read_b64_tr_b16 v[88:89], v185 offset:22240
	ds_read_b64_tr_b16 v[90:91], v185 offset:26848
	ds_read_b64_tr_b16 v[92:93], v185 offset:31456
	ds_read_b128 v[166:169], v188 offset:256
	ds_read_b128 v[170:173], v188 offset:320
	ds_read_b128 v[174:177], v188 offset:384
	ds_read_b128 v[178:181], v188 offset:448
	s_waitcnt vmcnt(6)
	ds_write_b128 v243, v[224:227] offset:17408
	ds_write_b128 v243, v[228:231] offset:26624
	ds_write_b128 v190, v[232:235] offset:35840
	ds_write_b128 v189, v[216:219]
	ds_write_b128 v189, v[220:223] offset:8704
	ds_write_b32 v191, v236
	s_add_i32 s64, s12, 3
	s_min_u32 s65, s64, 35
	s_sub_i32 s48, 3, s65
	s_sub_i32 s49, 39, s65
	s_cmp_lt_u32 s65, 4
	s_cselect_b32 s48, s48, s49
	s_cmp_eq_u32 s31, 0
	s_cselect_b32 s54, s65, s48
	s_lshl_b32 s48, s54, 6
	s_add_i32 s49, s33, s48
	s_add_i32 s48, s34, s48
	s_cmp_lt_u32 s54, 4
	s_cselect_b32 s55, s49, s48
	s_mul_i32 s48, s55, s30
	s_add_u32 s0, s16, s48
	s_addc_u32 s1, s17, 0
	s_add_u32 s2, s18, s48
	s_addc_u32 s3, s19, 0
	s_mul_i32 s48, s55, 0x1800
	s_add_u32 s4, s20, s48
	s_addc_u32 s5, s21, 0
	s_lshl_b32 s48, s54, 9
	s_add_u32 s6, s22, s48
	s_addc_u32 s7, s23, 0
	global_load_dwordx4 v[224:227], v244, s[2:3]
	global_load_dwordx4 v[228:231], v245, s[2:3]
	global_load_dwordx4 v[232:235], v246, s[4:5]
	global_load_dwordx4 v[216:219], v244, s[0:1]
	global_load_dwordx4 v[220:223], v245, s[0:1]
	global_load_dword v236, v194, s[6:7]
	s_waitcnt lgkmcnt(10)
	v_mfma_f32_16x16x32_bf16 v[2:5], v[62:65], v[126:129], v[2:5]
	v_mfma_f32_16x16x32_bf16 v[2:5], v[66:69], v[130:133], v[2:5]
	v_mfma_f32_16x16x32_bf16 v[6:9], v[70:73], v[126:129], v[6:9]
	v_mfma_f32_16x16x32_bf16 v[6:9], v[74:77], v[130:133], v[6:9]
	v_mfma_f32_16x16x32_bf16 v[10:13], v[78:81], v[126:129], v[10:13]
	v_mfma_f32_16x16x32_bf16 v[10:13], v[82:85], v[130:133], v[10:13]
	v_mfma_f32_16x16x32_bf16 v[14:17], v[86:89], v[126:129], v[14:17]
	v_mfma_f32_16x16x32_bf16 v[14:17], v[90:93], v[130:133], v[14:17]
	s_waitcnt lgkmcnt(6)
	s_nop 0
	v_pk_mul_f32 v[2:3], v[2:3], v[166:167]
	v_pk_mul_f32 v[4:5], v[4:5], v[168:169]
	v_pk_mul_f32 v[6:7], v[6:7], v[170:171]
	v_pk_mul_f32 v[8:9], v[8:9], v[172:173]
	v_pk_mul_f32 v[10:11], v[10:11], v[174:175]
	v_pk_mul_f32 v[12:13], v[12:13], v[176:177]
	v_pk_mul_f32 v[14:15], v[14:15], v[178:179]
	v_pk_mul_f32 v[16:17], v[16:17], v[180:181]
	v_cvt_pk_bf16_f32 v158, v2, v3
	v_cvt_pk_bf16_f32 v159, v4, v5
	v_cvt_pk_bf16_f32 v160, v6, v7
	v_cvt_pk_bf16_f32 v161, v8, v9
	v_cvt_pk_bf16_f32 v162, v10, v11
	v_cvt_pk_bf16_f32 v163, v12, v13
	v_cvt_pk_bf16_f32 v164, v14, v15
	v_cvt_pk_bf16_f32 v165, v16, v17
	ds_write_b128 v60, v[158:161]
	ds_write_b128 v60, v[162:165] offset:1024
	s_waitcnt lgkmcnt(0)
	s_barrier
	s_branch .Lp8_next_1

.Lp8_wd_8:
	ds_write_b128 v243, v[224:227] offset:17408
	ds_write_b128 v243, v[228:231] offset:26624
	ds_write_b128 v190, v[232:235] offset:35840
	ds_write_b128 v189, v[216:219]
	ds_write_b128 v189, v[220:223] offset:8704
	ds_write_b32 v191, v236
	s_add_i32 s64, s12, 3
	s_min_u32 s65, s64, 35
	s_sub_i32 s48, 3, s65
	s_sub_i32 s49, 39, s65
	s_cmp_lt_u32 s65, 4
	s_cselect_b32 s48, s48, s49
	s_cmp_eq_u32 s31, 0
	s_cselect_b32 s54, s65, s48
	s_lshl_b32 s48, s54, 6
	s_add_i32 s49, s33, s48
	s_add_i32 s48, s34, s48
	s_cmp_lt_u32 s54, 4
	s_cselect_b32 s55, s49, s48
	s_mul_i32 s48, s55, s30
	s_add_u32 s0, s16, s48
	s_addc_u32 s1, s17, 0
	s_add_u32 s2, s18, s48
	s_addc_u32 s3, s19, 0
	s_mul_i32 s48, s55, 0x1800
	s_add_u32 s4, s20, s48
	s_addc_u32 s5, s21, 0
	s_lshl_b32 s48, s54, 9
	s_add_u32 s6, s22, s48
	s_addc_u32 s7, s23, 0
	global_load_dwordx4 v[224:227], v244, s[2:3]
	global_load_dwordx4 v[228:231], v245, s[2:3]
	global_load_dwordx4 v[232:235], v246, s[4:5]
	global_load_dwordx4 v[216:219], v244, s[0:1]
	global_load_dwordx4 v[220:223], v245, s[0:1]
	global_load_dword v236, v194, s[6:7]
	s_waitcnt lgkmcnt(15)
	v_mfma_f32_16x16x32_bf16 v[42:45], v[166:169], v[62:65], 0
	v_mfma_f32_16x16x32_bf16 v[46:49], v[200:203], v[62:65], 0
	v_mfma_f32_16x16x32_bf16 v[42:45], v[170:173], v[66:69], v[42:45]
	v_mfma_f32_16x16x32_bf16 v[46:49], v[204:207], v[66:69], v[46:49]
	v_mfma_f32_16x16x32_bf16 v[42:45], v[174:177], v[70:73], v[42:45]
	v_mfma_f32_16x16x32_bf16 v[46:49], v[208:211], v[70:73], v[46:49]
	v_mfma_f32_16x16x32_bf16 v[42:45], v[178:181], v[74:77], v[42:45]
	v_mfma_f32_16x16x32_bf16 v[46:49], v[212:215], v[74:77], v[46:49]
	s_nop 6
	v_cndmask_b32_e64 v42, v42, 0, s[40:41]
	v_cndmask_b32_e64 v43, v43, 0, s[42:43]
	v_cndmask_b32_e64 v44, v44, 0, s[44:45]
	v_cndmask_b32_e64 v45, v45, 0, s[46:47]
	v_cndmask_b32_e64 v46, v46, 0, s[80:81]
	v_cndmask_b32_e64 v47, v47, 0, s[82:83]
	v_cndmask_b32_e64 v48, v48, 0, s[84:85]
	v_cndmask_b32_e64 v49, v49, 0, s[86:87]
	v_cvt_pk_bf16_f32 v50, v42, v43
	v_cvt_pk_bf16_f32 v51, v44, v45
	v_cvt_pk_bf16_f32 v52, v46, v47
	v_cvt_pk_bf16_f32 v53, v48, v49
	ds_write_b64 v57, v[50:51]
	ds_write_b64 v58, v[52:53]
	s_waitcnt lgkmcnt(0)
	s_barrier
	ds_read_b128 v[158:161], v61
	ds_read_b128 v[162:165], v61 offset:1024
	ds_read_b128 v[18:21], v59 offset:0
	ds_read_b128 v[22:25], v59 offset:7680
	ds_read_b128 v[26:29], v59 offset:7744
	ds_read_b128 v[166:169], v188 offset:0
	ds_read_b128 v[170:173], v188 offset:64
	ds_read_b128 v[174:177], v188 offset:128
	ds_read_b128 v[178:181], v188 offset:192
	s_waitcnt lgkmcnt(7)
	v_mfma_f32_16x16x32_bf16 v[34:37], v[150:153], v[94:97], 0
	v_mfma_f32_16x16x32_bf16 v[38:41], v[150:153], v[110:113], 0
	v_mfma_f32_16x16x32_bf16 v[34:37], v[154:157], v[98:101], v[34:37]
	v_mfma_f32_16x16x32_bf16 v[38:41], v[154:157], v[114:117], v[38:41]
	v_mfma_f32_16x16x32_bf16 v[34:37], v[158:161], v[102:105], v[34:37]
	v_mfma_f32_16x16x32_bf16 v[38:41], v[158:161], v[118:121], v[38:41]
	v_mfma_f32_16x16x32_bf16 v[34:37], v[162:165], v[106:109], v[34:37]
	v_mfma_f32_16x16x32_bf16 v[38:41], v[162:165], v[122:125], v[38:41]
	s_waitcnt lgkmcnt(4)
	v_mfma_f32_16x16x32_bf16 v[34:37], v[126:129], v[18:21], v[34:37]
	v_mfma_f32_16x16x32_bf16 v[38:41], v[126:129], v[22:25], v[38:41]
	v_mfma_f32_16x16x32_bf16 v[38:41], v[130:133], v[26:29], v[38:41]
	s_waitcnt lgkmcnt(0)
	s_nop 4
	v_cvt_pk_bf16_f32 v50, v34, v35
	v_cvt_pk_bf16_f32 v51, v36, v37
	global_store_dwordx2 v247, v[50:51], s[8:9]
	v_cvt_pk_bf16_f32 v52, v38, v39
	v_cvt_pk_bf16_f32 v53, v40, v41
	global_store_dwordx2 v247, v[52:53], s[10:11]
	v_pk_mul_f32 v[2:3], v[2:3], v[166:167]
	v_pk_mul_f32 v[4:5], v[4:5], v[168:169]
	v_pk_mul_f32 v[6:7], v[6:7], v[170:171]
	v_pk_mul_f32 v[8:9], v[8:9], v[172:173]
	v_pk_mul_f32 v[10:11], v[10:11], v[174:175]
	v_pk_mul_f32 v[12:13], v[12:13], v[176:177]
	v_pk_mul_f32 v[14:15], v[14:15], v[178:179]
	v_pk_mul_f32 v[16:17], v[16:17], v[180:181]
	v_cvt_pk_bf16_f32 v150, v2, v3
	v_cvt_pk_bf16_f32 v151, v4, v5
	v_cvt_pk_bf16_f32 v152, v6, v7
	v_cvt_pk_bf16_f32 v153, v8, v9
	v_cvt_pk_bf16_f32 v154, v10, v11
	v_cvt_pk_bf16_f32 v155, v12, v13
	v_cvt_pk_bf16_f32 v156, v14, v15
	v_cvt_pk_bf16_f32 v157, v16, v17
	ds_write_b128 v60, v[150:153]
	ds_write_b128 v60, v[154:157] offset:1024
	s_waitcnt lgkmcnt(0)
	s_barrier
	s_branch .Lp8_next_1

.Lp8_wd_10:
	ds_write_b128 v243, v[224:227] offset:17408
	ds_write_b128 v243, v[228:231] offset:26624
	ds_write_b128 v190, v[232:235] offset:35840
	ds_write_b128 v189, v[216:219]
	ds_write_b128 v189, v[220:223] offset:8704
	ds_write_b32 v191, v236
	s_add_i32 s64, s12, 3
	s_min_u32 s65, s64, 35
	s_sub_i32 s48, 3, s65
	s_sub_i32 s49, 39, s65
	s_cmp_lt_u32 s65, 4
	s_cselect_b32 s48, s48, s49
	s_cmp_eq_u32 s31, 0
	s_cselect_b32 s54, s65, s48
	s_lshl_b32 s48, s54, 6
	s_add_i32 s49, s33, s48
	s_add_i32 s48, s34, s48
	s_cmp_lt_u32 s54, 4
	s_cselect_b32 s55, s49, s48
	s_mul_i32 s48, s55, s30
	s_add_u32 s0, s16, s48
	s_addc_u32 s1, s17, 0
	s_add_u32 s2, s18, s48
	s_addc_u32 s3, s19, 0
	s_mul_i32 s48, s55, 0x1800
	s_add_u32 s4, s20, s48
	s_addc_u32 s5, s21, 0
	s_lshl_b32 s48, s54, 9
	s_add_u32 s6, s22, s48
	s_addc_u32 s7, s23, 0
	global_load_dwordx4 v[224:227], v244, s[2:3]
	global_load_dwordx4 v[228:231], v245, s[2:3]
	global_load_dwordx4 v[232:235], v246, s[4:5]
	global_load_dwordx4 v[216:219], v244, s[0:1]
	global_load_dwordx4 v[220:223], v245, s[0:1]
	global_load_dword v236, v194, s[6:7]
	s_waitcnt lgkmcnt(0)
	s_barrier
	v_mfma_f32_16x16x32_bf16 v[42:45], v[166:169], v[62:65], 0
	v_mfma_f32_16x16x32_bf16 v[46:49], v[200:203], v[62:65], 0
	v_mfma_f32_16x16x32_bf16 v[42:45], v[170:173], v[66:69], v[42:45]
	v_mfma_f32_16x16x32_bf16 v[46:49], v[204:207], v[66:69], v[46:49]
	v_mfma_f32_16x16x32_bf16 v[42:45], v[174:177], v[70:73], v[42:45]
	v_mfma_f32_16x16x32_bf16 v[46:49], v[208:211], v[70:73], v[46:49]
	v_mfma_f32_16x16x32_bf16 v[42:45], v[178:181], v[74:77], v[42:45]
	v_mfma_f32_16x16x32_bf16 v[46:49], v[212:215], v[74:77], v[46:49]
	s_nop 6
	v_cndmask_b32_e64 v42, v42, 0, s[40:41]
	v_cndmask_b32_e64 v43, v43, 0, s[42:43]
	v_cndmask_b32_e64 v44, v44, 0, s[44:45]
	v_cndmask_b32_e64 v45, v45, 0, s[46:47]
	v_cndmask_b32_e64 v46, v46, 0, s[80:81]
	v_cndmask_b32_e64 v47, v47, 0, s[82:83]
	v_cndmask_b32_e64 v48, v48, 0, s[84:85]
	v_cndmask_b32_e64 v49, v49, 0, s[86:87]
	v_cvt_pk_bf16_f32 v50, v42, v43
	v_cvt_pk_bf16_f32 v51, v44, v45
	v_cvt_pk_bf16_f32 v52, v46, v47
	v_cvt_pk_bf16_f32 v53, v48, v49
	ds_write_b64 v57, v[50:51]
	ds_write_b64 v58, v[52:53]
	ds_read_b128 v[166:169], v188 offset:256
	ds_read_b128 v[170:173], v188 offset:320
	ds_read_b128 v[174:177], v188 offset:384
	ds_read_b128 v[178:181], v188 offset:448
	s_mov_b64 s[76:77], s[8:9]
	s_mov_b64 s[78:79], s[10:11]
	s_waitcnt lgkmcnt(4)
	s_barrier
.Lp8_next_1:
	s_add_i32 s12, s12, 1
	s_cmp_lt_u32 s12, 36
	s_cbranch_scc1 .Lp8_step
	s_cmp_eq_u32 s37, 0
	s_cbranch_scc1 .Lp8_done
	ds_read_b128 v[18:21], v59 offset:2560
	ds_read_b128 v[22:25], v59 offset:5120
	ds_read_b128 v[26:29], v59 offset:5184
	s_waitcnt lgkmcnt(0)
	v_mfma_f32_16x16x32_bf16 v[34:37], v[126:129], v[18:21], v[34:37]
	v_mfma_f32_16x16x32_bf16 v[38:41], v[126:129], v[22:25], v[38:41]
	v_mfma_f32_16x16x32_bf16 v[38:41], v[130:133], v[26:29], v[38:41]
	s_nop 5
	v_cvt_pk_bf16_f32 v50, v34, v35
	v_cvt_pk_bf16_f32 v51, v36, v37
	global_store_dwordx2 v247, v[50:51], s[76:77]
	v_cvt_pk_bf16_f32 v52, v38, v39
	v_cvt_pk_bf16_f32 v53, v40, v41
	global_store_dwordx2 v247, v[52:53], s[78:79]
	v_pk_mul_f32 v[2:3], v[2:3], v[166:167]
	v_pk_mul_f32 v[4:5], v[4:5], v[168:169]
	v_pk_mul_f32 v[6:7], v[6:7], v[170:171]
	v_pk_mul_f32 v[8:9], v[8:9], v[172:173]
	v_pk_mul_f32 v[10:11], v[10:11], v[174:175]
	v_pk_mul_f32 v[12:13], v[12:13], v[176:177]
	v_pk_mul_f32 v[14:15], v[14:15], v[178:179]
	v_pk_mul_f32 v[16:17], v[16:17], v[180:181]
	v_cvt_pk_bf16_f32 v158, v2, v3
	v_cvt_pk_bf16_f32 v159, v4, v5
	v_cvt_pk_bf16_f32 v160, v6, v7
	v_cvt_pk_bf16_f32 v161, v8, v9
	v_cvt_pk_bf16_f32 v162, v10, v11
	v_cvt_pk_bf16_f32 v163, v12, v13
	v_cvt_pk_bf16_f32 v164, v14, v15
	v_cvt_pk_bf16_f32 v165, v16, v17
	ds_write_b128 v60, v[158:161]
	ds_write_b128 v60, v[162:165] offset:1024
